# saddr + 32-bit voffset LDS-DMA loads extended to the GLU, merge and output GEMM K-loops (loader wave has no per-load 64-bit VALU add)
# baseline (speedup 1.0000x reference)
; #define PG8_STAGE(bufoff, gbase, voff) do { _Pragma("unroll") for (int _i = 0; _i < 2; ++_i) \
;         __builtin_amdgcn_global_load_lds((const unsigned*)((const char*)(gbase) + (voff)[_i]), (LAS unsigned*)(lds + (bufoff) + ldsw + _i * 8192), 16, 0, 0); } while (0)
; #define PG8_LDA(dst, b, h) do { _Pragma("unroll") for (int m = 0; m < 4; ++m) _Pragma("unroll") for (int k = 0; k < 2; ++k) dst[m][k] = *(const LAS bf16x8*)(lds + PG8_SA(b, h) + aoff + m * 2048 + k * 1024); } while (0)
; #define PG8_WAIT_V(n) asm volatile("s_waitcnt vmcnt(" #n ")" ::: "memory")
; template <class Epi, class Sched, bool ALIGN_EPI = false, bool SP2 = false, bool TWOA = false, bool AGM = false>
; __device__ __forceinline__ void gemm_phase(LAS unsigned char* lds, const Gemm g, const Sched& S, const Epi& E, int wid) {
;     ...
;         const bool has_next = S.next(ui + 1, nxt);
;         const char* nA = has_next ? (const char*)g.A + (size_t)nxt.pm * tstepA : cA; const char* nB = has_next ? (const char*)g.Bt + (size_t)nxt.pn * tstep : cB;
;         for (int t = 0; t < nt; t += 2) {
;             const bool last = (t == nt - 2);
;             const char* cA2 = TWOA ? (const char*)g.A2 + (cA - (const char*)g.A) - (size_t)nh * kstepA : cA;
;             const char* a1_ = (TWOA && t + 1 >= nh ? cA2 : cA) + (size_t)(t + 1) * kstepA;
;             const char* a2_ = last ? nA : (TWOA && t + 2 >= nh ? cA2 : cA) + (size_t)(t + 2) * kstepA; const char* a1 = a1_; const char* a2 = a2_; const char* b2 = last ? nB : cB + (size_t)(t + 2) * kstep;
;             if constexpr (TWOA) { asm volatile("" : "+s"(a1)); asm volatile("" : "+s"(a2)); }
;             const char* a3 = a2 + kstepA; const char* b3 = b2 + kstep;
;             if (last && has_next) S.a_ready(nxt);
;             if constexpr (has_mid<Epi>::value) { if (t == nh) E.mid(acc, cur, wr, wc, fr, fq); }
;             if constexpr (SP2) {
;             PG8_LDB(B0, 0, 0); PG8_LDB(B1, 0, 1); PG8_SCHED; PG8_LDA(At, 0, 0); PG8_STAGE(PG8_SA(1, 1), a1 + hstepA, voffA);
;             PG8_WAIT_V(8); PG8_WAIT_L(0); PG8_BAR; PG8_MMA(0, 0, At, B0); PG8_MMA(0, 1, At, B1); PG8_BAR; PG8_SCHED;
;             PG8_LDA(At, 0, 1); PG8_STAGE(PG8_SB(0, 0), b2, voffB); PG8_STAGE(PG8_SB(0, 1), b2 + hstep, voffB); PG8_STAGE(PG8_SA(0, 0), a2, voffA);
;             PG8_WAIT_V(8); PG8_WAIT_L(0); PG8_BAR; PG8_MMA(1, 0, At, B0); PG8_MMA(1, 1, At, B1); PG8_BAR; PG8_SCHED;
.LBB0_753:
	ds_read_b128 v[146:149], v152
	ds_read_b128 v[156:159], v152 offset:1024
	ds_read_b128 v[160:163], v152 offset:2048
	ds_read_b128 v[164:167], v152 offset:3072
	ds_read_b128 v[168:171], v153
	ds_read_b128 v[172:175], v153 offset:1024
	ds_read_b128 v[176:179], v153 offset:2048
	ds_read_b128 v[180:183], v153 offset:3072
	s_add_u32 s38, s36, 0x600000
	s_addc_u32 s39, s37, 0
	s_cmp_eq_u32 s75, 28
	s_cselect_b32 s44, s71, s38
	s_cselect_b32 s45, s25, s39
	s_cselect_b32 s42, s72, s73
	s_cselect_b32 s43, s23, s74
	s_add_u32 s40, s44, 0x300000
	s_addc_u32 s41, s45, 0
	s_add_i32 m0, s50, 0xc000
	ds_read_b128 v[184:187], v154
	ds_read_b128 v[188:191], v154 offset:1024
	ds_read_b128 v[192:195], v154 offset:2048
	ds_read_b128 v[196:199], v154 offset:3072
	ds_read_b128 v[200:203], v154 offset:4096
	ds_read_b128 v[204:207], v154 offset:5120
	ds_read_b128 v[208:211], v154 offset:6144
	ds_read_b128 v[212:215], v154 offset:7168
	global_load_lds_dwordx4 v136, s[36:37]
	s_add_i32 m0, s50, 0xe000
	s_nop 0
	global_load_lds_dwordx4 v138, s[36:37]
	s_waitcnt vmcnt(8)
	s_waitcnt lgkmcnt(0)
	s_barrier
	s_setprio 1
	s_waitcnt lgkmcnt(0)
	v_mfma_f32_16x16x32_bf16 v[116:119], v[146:149], v[184:187], v[116:119]
	v_mfma_f32_16x16x32_bf16 v[112:115], v[160:163], v[184:187], v[112:115]
	v_mfma_f32_16x16x32_bf16 v[100:103], v[146:149], v[192:195], v[100:103]
	v_mfma_f32_16x16x32_bf16 v[96:99], v[160:163], v[192:195], v[96:99]
	v_mfma_f32_16x16x32_bf16 v[84:87], v[146:149], v[200:203], v[84:87]
	v_mfma_f32_16x16x32_bf16 v[80:83], v[160:163], v[200:203], v[80:83]
	v_mfma_f32_16x16x32_bf16 v[68:71], v[146:149], v[208:211], v[68:71]
	v_mfma_f32_16x16x32_bf16 v[64:67], v[160:163], v[208:211], v[64:67]
	v_mfma_f32_16x16x32_bf16 v[116:119], v[156:159], v[188:191], v[116:119]
	v_mfma_f32_16x16x32_bf16 v[112:115], v[164:167], v[188:191], v[112:115]
	v_mfma_f32_16x16x32_bf16 v[100:103], v[156:159], v[196:199], v[100:103]
	v_mfma_f32_16x16x32_bf16 v[96:99], v[164:167], v[196:199], v[96:99]
	v_mfma_f32_16x16x32_bf16 v[84:87], v[156:159], v[204:207], v[84:87]
	v_mfma_f32_16x16x32_bf16 v[80:83], v[164:167], v[204:207], v[80:83]
	v_mfma_f32_16x16x32_bf16 v[68:71], v[156:159], v[212:215], v[68:71]
	v_mfma_f32_16x16x32_bf16 v[64:67], v[164:167], v[212:215], v[64:67]
	s_setprio 0
	s_setprio 1
	v_mfma_f32_16x16x32_bf16 v[124:127], v[168:171], v[184:187], v[124:127]
	v_mfma_f32_16x16x32_bf16 v[120:123], v[176:179], v[184:187], v[120:123]
	v_mfma_f32_16x16x32_bf16 v[108:111], v[168:171], v[192:195], v[108:111]
	v_mfma_f32_16x16x32_bf16 v[104:107], v[176:179], v[192:195], v[104:107]
	v_mfma_f32_16x16x32_bf16 v[92:95], v[168:171], v[200:203], v[92:95]
	v_mfma_f32_16x16x32_bf16 v[88:91], v[176:179], v[200:203], v[88:91]
	v_mfma_f32_16x16x32_bf16 v[76:79], v[168:171], v[208:211], v[76:79]
	v_mfma_f32_16x16x32_bf16 v[72:75], v[176:179], v[208:211], v[72:75]
	v_mfma_f32_16x16x32_bf16 v[124:127], v[172:175], v[188:191], v[124:127]
	v_mfma_f32_16x16x32_bf16 v[120:123], v[180:183], v[188:191], v[120:123]
	v_mfma_f32_16x16x32_bf16 v[108:111], v[172:175], v[196:199], v[108:111]
	v_mfma_f32_16x16x32_bf16 v[104:107], v[180:183], v[196:199], v[104:107]
	v_mfma_f32_16x16x32_bf16 v[92:95], v[172:175], v[204:207], v[92:95]
	v_mfma_f32_16x16x32_bf16 v[88:91], v[180:183], v[204:207], v[88:91]
	v_mfma_f32_16x16x32_bf16 v[76:79], v[172:175], v[212:215], v[76:79]
	v_mfma_f32_16x16x32_bf16 v[72:75], v[180:183], v[212:215], v[72:75]
	s_setprio 0
	s_barrier
	s_add_i32 s34, s65, s3
	s_add_u32 s98, s42, s12
	s_addc_u32 s99, s43, s13
	s_mov_b32 m0, s34
	ds_read_b128 v[184:187], v154 offset:16384
	ds_read_b128 v[188:191], v154 offset:17408
	ds_read_b128 v[192:195], v154 offset:18432
	ds_read_b128 v[196:199], v154 offset:19456
	ds_read_b128 v[200:203], v154 offset:20480
	ds_read_b128 v[204:207], v154 offset:21504
	ds_read_b128 v[208:211], v154 offset:22528
	ds_read_b128 v[212:215], v154 offset:23552
	global_load_lds_dwordx4 v132, s[42:43]
	s_add_i32 m0, s34, 0x2000
	s_add_u32 s34, s42, 0x80000
	s_addc_u32 s35, s43, 0
	s_add_i32 s36, s66, s3
	global_load_lds_dwordx4 v128, s[42:43]
	s_mov_b32 m0, s36
	s_nop 0
	global_load_lds_dwordx4 v132, s[34:35]
	s_add_i32 m0, s36, 0x2000
	s_nop 0
	global_load_lds_dwordx4 v128, s[34:35]
	s_mov_b32 m0, s50
	s_nop 0
	global_load_lds_dwordx4 v134, s[44:45]
	s_mov_b32 m0, s51
	s_nop 0
	global_load_lds_dwordx4 v130, s[44:45]
	s_waitcnt vmcnt(8)
	s_waitcnt lgkmcnt(0)
	s_barrier
	s_setprio 1
	s_waitcnt lgkmcnt(0)
	v_mfma_f32_16x16x32_bf16 v[52:55], v[146:149], v[184:187], v[52:55]
	v_mfma_f32_16x16x32_bf16 v[48:51], v[160:163], v[184:187], v[48:51]
	v_mfma_f32_16x16x32_bf16 v[36:39], v[146:149], v[192:195], v[36:39]
	v_mfma_f32_16x16x32_bf16 v[32:35], v[160:163], v[192:195], v[32:35]
	v_mfma_f32_16x16x32_bf16 v[20:23], v[146:149], v[200:203], v[20:23]
	v_mfma_f32_16x16x32_bf16 v[16:19], v[160:163], v[200:203], v[16:19]
	v_mfma_f32_16x16x32_bf16 v[4:7], v[146:149], v[208:211], v[4:7]
	v_mfma_f32_16x16x32_bf16 v[0:3], v[160:163], v[208:211], v[0:3]
	v_mfma_f32_16x16x32_bf16 v[52:55], v[156:159], v[188:191], v[52:55]
	v_mfma_f32_16x16x32_bf16 v[48:51], v[164:167], v[188:191], v[48:51]
	v_mfma_f32_16x16x32_bf16 v[36:39], v[156:159], v[196:199], v[36:39]
	v_mfma_f32_16x16x32_bf16 v[32:35], v[164:167], v[196:199], v[32:35]
	v_mfma_f32_16x16x32_bf16 v[20:23], v[156:159], v[204:207], v[20:23]
	v_mfma_f32_16x16x32_bf16 v[16:19], v[164:167], v[204:207], v[16:19]
	v_mfma_f32_16x16x32_bf16 v[4:7], v[156:159], v[212:215], v[4:7]
	v_mfma_f32_16x16x32_bf16 v[0:3], v[164:167], v[212:215], v[0:3]
	s_setprio 0
	s_setprio 1
	v_mfma_f32_16x16x32_bf16 v[60:63], v[168:171], v[184:187], v[60:63]
	v_mfma_f32_16x16x32_bf16 v[56:59], v[176:179], v[184:187], v[56:59]
	v_mfma_f32_16x16x32_bf16 v[44:47], v[168:171], v[192:195], v[44:47]
	v_mfma_f32_16x16x32_bf16 v[40:43], v[176:179], v[192:195], v[40:43]
	v_mfma_f32_16x16x32_bf16 v[28:31], v[168:171], v[200:203], v[28:31]
	v_mfma_f32_16x16x32_bf16 v[24:27], v[176:179], v[200:203], v[24:27]
	v_mfma_f32_16x16x32_bf16 v[12:15], v[168:171], v[208:211], v[12:15]
	v_mfma_f32_16x16x32_bf16 v[8:11], v[176:179], v[208:211], v[8:11]
	v_mfma_f32_16x16x32_bf16 v[60:63], v[172:175], v[188:191], v[60:63]
	v_mfma_f32_16x16x32_bf16 v[56:59], v[180:183], v[188:191], v[56:59]
	v_mfma_f32_16x16x32_bf16 v[44:47], v[172:175], v[196:199], v[44:47]
	v_mfma_f32_16x16x32_bf16 v[40:43], v[180:183], v[196:199], v[40:43]
	v_mfma_f32_16x16x32_bf16 v[28:31], v[172:175], v[204:207], v[28:31]
	v_mfma_f32_16x16x32_bf16 v[24:27], v[180:183], v[204:207], v[24:27]
	v_mfma_f32_16x16x32_bf16 v[12:15], v[172:175], v[212:215], v[12:15]
	v_mfma_f32_16x16x32_bf16 v[8:11], v[180:183], v[212:215], v[8:11]
	s_setprio 0
	s_barrier
; #define PG8_STAGE(bufoff, gbase, voff) do { _Pragma("unroll") for (int _i = 0; _i < 2; ++_i) \
;         __builtin_amdgcn_global_load_lds((const unsigned*)((const char*)(gbase) + (voff)[_i]), (LAS unsigned*)(lds + (bufoff) + ldsw + _i * 8192), 16, 0, 0); } while (0)
; #define PG8_LDA(dst, b, h) do { _Pragma("unroll") for (int m = 0; m < 4; ++m) _Pragma("unroll") for (int k = 0; k < 2; ++k) dst[m][k] = *(const LAS bf16x8*)(lds + PG8_SA(b, h) + aoff + m * 2048 + k * 1024); } while (0)
; #define PG8_LDB(dst, b, h) do { _Pragma("unroll") for (int n = 0; n < 2; ++n) _Pragma("unroll") for (int k = 0; k < 2; ++k) dst[n][k] = *(const LAS bf16x8*)(lds + PG8_SB(b, h) + boff + n * 2048 + k * 1024); } while (0)
; #define PG8_MMA(ai, bj, At, Bt) do { __builtin_amdgcn_s_setprio(1); _Pragma("unroll") for (int m = 0; m < 4; ++m) _Pragma("unroll") for (int n = 0; n < 2; ++n) _Pragma("unroll") for (int k = 0; k < 2; ++k) \
;         acc[ai][bj][m][n] = __builtin_amdgcn_mfma_f32_16x16x32_bf16(Bt[n][k], At[m][k], acc[ai][bj][m][n], 0, 0, 0); __builtin_amdgcn_s_setprio(0); } while (0)
; #define PG8_WAIT_V(n) asm volatile("s_waitcnt vmcnt(" #n ")" ::: "memory")
; #define PG8_WAIT_L(n) asm volatile("s_waitcnt lgkmcnt(" #n ")" ::: "memory")
; #define PG8_BAR __builtin_amdgcn_s_barrier()
; #define PG8_SCHED __builtin_amdgcn_sched_barrier(0)
; template <class Epi, class Sched, bool ALIGN_EPI = false, bool SP2 = false, bool TWOA = false, bool AGM = false>
; __device__ __forceinline__ void gemm_phase(LAS unsigned char* lds, const Gemm g, const Sched& S, const Epi& E, int wid) {
;     ...
;         for (int t = 0; t < nt; t += 2) {
;             const bool last = (t == nt - 2);
;     ...
;             PG8_LDB(B0, 1, 0); PG8_LDB(B1, 1, 1); PG8_SCHED; PG8_LDA(At, 1, 0); PG8_STAGE(PG8_SA(0, 1), a2 + hstepA, voffA);
;             PG8_WAIT_V(8); PG8_WAIT_L(0); PG8_BAR; PG8_MMA(0, 0, At, B0); PG8_MMA(0, 1, At, B1); PG8_BAR; PG8_SCHED;
;             PG8_LDA(At, 1, 1); PG8_STAGE(PG8_SB(1, 0), b3, voffB); PG8_STAGE(PG8_SB(1, 1), b3 + hstep, voffB); PG8_STAGE(PG8_SA(1, 0), a3, voffA);
;             PG8_WAIT_V(8); PG8_WAIT_L(0); PG8_BAR; PG8_MMA(1, 0, At, B0); PG8_MMA(1, 1, At, B1); PG8_BAR; PG8_SCHED;
	s_add_i32 s36, 0, 0x18000
	v_add_u32_e32 v155, s36, v151
	s_add_i32 s37, 0, 0x1c000
	ds_read_b128 v[146:149], v155
	ds_read_b128 v[156:159], v155 offset:1024
	ds_read_b128 v[160:163], v155 offset:2048
	ds_read_b128 v[164:167], v155 offset:3072
	v_add_u32_e32 v155, s37, v151
	ds_read_b128 v[168:171], v155
	ds_read_b128 v[172:175], v155 offset:1024
	ds_read_b128 v[176:179], v155 offset:2048
	ds_read_b128 v[180:183], v155 offset:3072
	s_add_u32 s34, s44, 0x1000
	s_addc_u32 s35, s45, 0
	s_mov_b32 m0, s52
	ds_read_b128 v[184:187], v154 offset:32768
	ds_read_b128 v[188:191], v154 offset:33792
	ds_read_b128 v[192:195], v154 offset:34816
	ds_read_b128 v[196:199], v154 offset:35840
	ds_read_b128 v[200:203], v154 offset:36864
	ds_read_b128 v[204:207], v154 offset:37888
	ds_read_b128 v[208:211], v154 offset:38912
	ds_read_b128 v[212:215], v154 offset:39936
	global_load_lds_dwordx4 v134, s[34:35]
	s_mov_b32 m0, s53
	s_nop 0
	global_load_lds_dwordx4 v130, s[34:35]
	s_waitcnt vmcnt(8)
	s_waitcnt lgkmcnt(0)
	s_barrier
	s_setprio 1
	s_waitcnt lgkmcnt(0)
	v_mfma_f32_16x16x32_bf16 v[116:119], v[146:149], v[184:187], v[116:119]
	v_mfma_f32_16x16x32_bf16 v[112:115], v[160:163], v[184:187], v[112:115]
	v_mfma_f32_16x16x32_bf16 v[100:103], v[146:149], v[192:195], v[100:103]
	v_mfma_f32_16x16x32_bf16 v[96:99], v[160:163], v[192:195], v[96:99]
	v_mfma_f32_16x16x32_bf16 v[84:87], v[146:149], v[200:203], v[84:87]
	v_mfma_f32_16x16x32_bf16 v[80:83], v[160:163], v[200:203], v[80:83]
	v_mfma_f32_16x16x32_bf16 v[68:71], v[146:149], v[208:211], v[68:71]
	v_mfma_f32_16x16x32_bf16 v[64:67], v[160:163], v[208:211], v[64:67]
	v_mfma_f32_16x16x32_bf16 v[116:119], v[156:159], v[188:191], v[116:119]
	v_mfma_f32_16x16x32_bf16 v[112:115], v[164:167], v[188:191], v[112:115]
	v_mfma_f32_16x16x32_bf16 v[100:103], v[156:159], v[196:199], v[100:103]
	v_mfma_f32_16x16x32_bf16 v[96:99], v[164:167], v[196:199], v[96:99]
	v_mfma_f32_16x16x32_bf16 v[84:87], v[156:159], v[204:207], v[84:87]
	v_mfma_f32_16x16x32_bf16 v[80:83], v[164:167], v[204:207], v[80:83]
	v_mfma_f32_16x16x32_bf16 v[68:71], v[156:159], v[212:215], v[68:71]
	v_mfma_f32_16x16x32_bf16 v[64:67], v[164:167], v[212:215], v[64:67]
	s_setprio 0
	s_setprio 1
	v_mfma_f32_16x16x32_bf16 v[124:127], v[168:171], v[184:187], v[124:127]
	v_mfma_f32_16x16x32_bf16 v[120:123], v[176:179], v[184:187], v[120:123]
	v_mfma_f32_16x16x32_bf16 v[108:111], v[168:171], v[192:195], v[108:111]
	v_mfma_f32_16x16x32_bf16 v[104:107], v[176:179], v[192:195], v[104:107]
	v_mfma_f32_16x16x32_bf16 v[92:95], v[168:171], v[200:203], v[92:95]
	v_mfma_f32_16x16x32_bf16 v[88:91], v[176:179], v[200:203], v[88:91]
	v_mfma_f32_16x16x32_bf16 v[76:79], v[168:171], v[208:211], v[76:79]
	v_mfma_f32_16x16x32_bf16 v[72:75], v[176:179], v[208:211], v[72:75]
	v_mfma_f32_16x16x32_bf16 v[124:127], v[172:175], v[188:191], v[124:127]
	v_mfma_f32_16x16x32_bf16 v[120:123], v[180:183], v[188:191], v[120:123]
	v_mfma_f32_16x16x32_bf16 v[108:111], v[172:175], v[196:199], v[108:111]
	v_mfma_f32_16x16x32_bf16 v[104:107], v[180:183], v[196:199], v[104:107]
	v_mfma_f32_16x16x32_bf16 v[92:95], v[172:175], v[204:207], v[92:95]
	v_mfma_f32_16x16x32_bf16 v[88:91], v[180:183], v[204:207], v[88:91]
	v_mfma_f32_16x16x32_bf16 v[76:79], v[172:175], v[212:215], v[76:79]
	v_mfma_f32_16x16x32_bf16 v[72:75], v[180:183], v[212:215], v[72:75]
	s_setprio 0
	s_barrier
	s_add_i32 s34, s36, s3
	s_mov_b32 m0, s34
	ds_read_b128 v[184:187], v154 offset:49152
	ds_read_b128 v[188:191], v154 offset:50176
	ds_read_b128 v[192:195], v154 offset:51200
	ds_read_b128 v[196:199], v154 offset:52224
	ds_read_b128 v[200:203], v154 offset:53248
	ds_read_b128 v[204:207], v154 offset:54272
	ds_read_b128 v[208:211], v154 offset:55296
	ds_read_b128 v[212:215], v154 offset:56320
	global_load_lds_dwordx4 v132, s[98:99]
	s_add_i32 m0, s34, 0x2000
	s_add_u32 s34, s42, 0x80080
	s_addc_u32 s35, s43, 0
	s_add_i32 s36, s37, s3
	global_load_lds_dwordx4 v128, s[98:99]
	s_mov_b32 m0, s36
	s_nop 0
	global_load_lds_dwordx4 v132, s[34:35]
	s_add_i32 m0, s36, 0x2000
	s_nop 0
	global_load_lds_dwordx4 v128, s[34:35]
	s_mov_b32 m0, s55
	s_nop 0
	global_load_lds_dwordx4 v134, s[40:41]
	s_mov_b32 m0, s56
	s_nop 0
	global_load_lds_dwordx4 v130, s[40:41]
	s_waitcnt vmcnt(8)
	s_waitcnt lgkmcnt(0)
	s_barrier
	s_setprio 1
	s_waitcnt lgkmcnt(0)
	v_mfma_f32_16x16x32_bf16 v[52:55], v[146:149], v[184:187], v[52:55]
	v_mfma_f32_16x16x32_bf16 v[48:51], v[160:163], v[184:187], v[48:51]
	v_mfma_f32_16x16x32_bf16 v[36:39], v[146:149], v[192:195], v[36:39]
	v_mfma_f32_16x16x32_bf16 v[32:35], v[160:163], v[192:195], v[32:35]
	v_mfma_f32_16x16x32_bf16 v[20:23], v[146:149], v[200:203], v[20:23]
	v_mfma_f32_16x16x32_bf16 v[16:19], v[160:163], v[200:203], v[16:19]
	v_mfma_f32_16x16x32_bf16 v[4:7], v[146:149], v[208:211], v[4:7]
	v_mfma_f32_16x16x32_bf16 v[0:3], v[160:163], v[208:211], v[0:3]
	v_mfma_f32_16x16x32_bf16 v[52:55], v[156:159], v[188:191], v[52:55]
	v_mfma_f32_16x16x32_bf16 v[48:51], v[164:167], v[188:191], v[48:51]
	v_mfma_f32_16x16x32_bf16 v[36:39], v[156:159], v[196:199], v[36:39]
	v_mfma_f32_16x16x32_bf16 v[32:35], v[164:167], v[196:199], v[32:35]
	v_mfma_f32_16x16x32_bf16 v[20:23], v[156:159], v[204:207], v[20:23]
	v_mfma_f32_16x16x32_bf16 v[16:19], v[164:167], v[204:207], v[16:19]
	v_mfma_f32_16x16x32_bf16 v[4:7], v[156:159], v[212:215], v[4:7]
	v_mfma_f32_16x16x32_bf16 v[0:3], v[164:167], v[212:215], v[0:3]
	s_setprio 0
	s_setprio 1
	v_mfma_f32_16x16x32_bf16 v[60:63], v[168:171], v[184:187], v[60:63]
	v_mfma_f32_16x16x32_bf16 v[56:59], v[176:179], v[184:187], v[56:59]
	v_mfma_f32_16x16x32_bf16 v[44:47], v[168:171], v[192:195], v[44:47]
	v_mfma_f32_16x16x32_bf16 v[40:43], v[176:179], v[192:195], v[40:43]
	v_mfma_f32_16x16x32_bf16 v[28:31], v[168:171], v[200:203], v[28:31]
	v_mfma_f32_16x16x32_bf16 v[24:27], v[176:179], v[200:203], v[24:27]
	v_mfma_f32_16x16x32_bf16 v[12:15], v[168:171], v[208:211], v[12:15]
	v_mfma_f32_16x16x32_bf16 v[8:11], v[176:179], v[208:211], v[8:11]
	v_mfma_f32_16x16x32_bf16 v[60:63], v[172:175], v[188:191], v[60:63]
	v_mfma_f32_16x16x32_bf16 v[56:59], v[180:183], v[188:191], v[56:59]
	v_mfma_f32_16x16x32_bf16 v[44:47], v[172:175], v[196:199], v[44:47]
	v_mfma_f32_16x16x32_bf16 v[40:43], v[180:183], v[196:199], v[40:43]
	v_mfma_f32_16x16x32_bf16 v[28:31], v[172:175], v[204:207], v[28:31]
	v_mfma_f32_16x16x32_bf16 v[24:27], v[180:183], v[204:207], v[24:27]
	v_mfma_f32_16x16x32_bf16 v[12:15], v[172:175], v[212:215], v[12:15]
	v_mfma_f32_16x16x32_bf16 v[8:11], v[180:183], v[212:215], v[8:11]
	s_setprio 0
	s_barrier
	s_add_i32 s75, s75, 2
	s_add_u32 s73, s73, 0x100
	s_addc_u32 s74, s74, 0
	s_cmp_gt_u32 s75, 29
	s_mov_b64 s[36:37], s[38:39]
	s_cbranch_scc0 .LBB0_753
	s_and_b64 vcc, exec, s[20:21]
	s_cbranch_vccz .LBB0_756
	s_barrier

; #define PG8_STAGE(bufoff, gbase, voff) do { _Pragma("unroll") for (int _i = 0; _i < 2; ++_i) \
;         __builtin_amdgcn_global_load_lds((const unsigned*)((const char*)(gbase) + (voff)[_i]), (LAS unsigned*)(lds + (bufoff) + ldsw + _i * 8192), 16, 0, 0); } while (0)
; #define PG8_LDA(dst, b, h) do { _Pragma("unroll") for (int m = 0; m < 4; ++m) _Pragma("unroll") for (int k = 0; k < 2; ++k) dst[m][k] = *(const LAS bf16x8*)(lds + PG8_SA(b, h) + aoff + m * 2048 + k * 1024); } while (0)
; #define PG8_LDB(dst, b, h) do { _Pragma("unroll") for (int n = 0; n < 2; ++n) _Pragma("unroll") for (int k = 0; k < 2; ++k) dst[n][k] = *(const LAS bf16x8*)(lds + PG8_SB(b, h) + boff + n * 2048 + k * 1024); } while (0)
; #define PG8_WAIT_V(n) asm volatile("s_waitcnt vmcnt(" #n ")" ::: "memory")
; #define PG8_WAIT_L(n) asm volatile("s_waitcnt lgkmcnt(" #n ")" ::: "memory")
; template <class Epi, class Sched, bool ALIGN_EPI = false, bool SP2 = false, bool TWOA = false, bool AGM = false>
; __device__ __forceinline__ void gemm_phase(LAS unsigned char* lds, const Gemm g, const Sched& S, const Epi& E, int wid) {
;     ...
;             const char* cA2 = TWOA ? (const char*)g.A2 + (cA - (const char*)g.A) - (size_t)nh * kstepA : cA;
;             const char* a1_ = (TWOA && t + 1 >= nh ? cA2 : cA) + (size_t)(t + 1) * kstepA;
;             const char* a2_ = last ? nA : (TWOA && t + 2 >= nh ? cA2 : cA) + (size_t)(t + 2) * kstepA; const char* a1 = a1_; const char* a2 = a2_; const char* b2 = last ? nB : cB + (size_t)(t + 2) * kstep;
;             if constexpr (TWOA) { asm volatile("" : "+s"(a1)); asm volatile("" : "+s"(a2)); }
;             const char* a3 = a2 + kstepA; const char* b3 = b2 + kstep;
;             if (last && has_next) S.a_ready(nxt);
;             if constexpr (has_mid<Epi>::value) { if (t == nh) E.mid(acc, cur, wr, wc, fr, fq); }
;             if constexpr (SP2) {
;             PG8_LDB(B0, 0, 0); PG8_LDB(B1, 0, 1); PG8_SCHED; PG8_LDA(At, 0, 0); PG8_STAGE(PG8_SA(1, 1), a1 + hstepA, voffA);
;             PG8_WAIT_V(8); PG8_WAIT_L(0); PG8_BAR; PG8_MMA(0, 0, At, B0); PG8_MMA(0, 1, At, B1); PG8_BAR; PG8_SCHED;
;             PG8_LDA(At, 0, 1); PG8_STAGE(PG8_SB(0, 0), b2, voffB); PG8_STAGE(PG8_SB(0, 1), b2 + hstep, voffB); PG8_STAGE(PG8_SA(0, 0), a2, voffA);
;             PG8_WAIT_V(8); PG8_WAIT_L(0); PG8_BAR; PG8_MMA(1, 0, At, B0); PG8_MMA(1, 1, At, B1); PG8_BAR; PG8_SCHED;
.LBB0_826:
	v_add_u32_e32 v1, s65, v153
	ds_read_b128 v[132:135], v1
	ds_read_b128 v[136:139], v1 offset:1024
	ds_read_b128 v[158:161], v1 offset:2048
	ds_read_b128 v[162:165], v1 offset:3072
	v_add_u32_e32 v1, s66, v153
	ds_read_b128 v[166:169], v1
	ds_read_b128 v[170:173], v1 offset:1024
	ds_read_b128 v[174:177], v1 offset:2048
	ds_read_b128 v[178:181], v1 offset:3072
	s_add_u32 s74, s71, s36
	s_addc_u32 s75, s72, s37
	s_and_b64 s[34:35], s[42:43], exec
	s_cselect_b32 s43, s23, s75
	s_cselect_b32 s42, s68, s74
	s_add_u32 s34, s40, 0x80000
	s_addc_u32 s35, s41, 0
	s_add_i32 m0, s50, 0xc000
	ds_read_b128 v[182:185], v156
	ds_read_b128 v[186:189], v156 offset:1024
	ds_read_b128 v[190:193], v156 offset:2048
	ds_read_b128 v[194:197], v156 offset:3072
	ds_read_b128 v[198:201], v156 offset:4096
	ds_read_b128 v[202:205], v156 offset:5120
	ds_read_b128 v[206:209], v156 offset:6144
	ds_read_b128 v[210:213], v156 offset:7168
	global_load_lds_dwordx4 v146, s[34:35]
	s_add_i32 m0, s50, 0xe000
	s_nop 0
	global_load_lds_dwordx4 v142, s[34:35]
	s_waitcnt vmcnt(8)
	s_waitcnt lgkmcnt(0)
	s_barrier
	s_setprio 1
	s_waitcnt lgkmcnt(0)
	v_mfma_f32_16x16x32_bf16 v[128:131], v[132:135], v[182:185], v[128:131]
	v_mfma_f32_16x16x32_bf16 v[124:127], v[158:161], v[182:185], v[124:127]
	v_mfma_f32_16x16x32_bf16 v[112:115], v[132:135], v[190:193], v[112:115]
	v_mfma_f32_16x16x32_bf16 v[108:111], v[158:161], v[190:193], v[108:111]
	v_mfma_f32_16x16x32_bf16 v[96:99], v[132:135], v[198:201], v[96:99]
	v_mfma_f32_16x16x32_bf16 v[92:95], v[158:161], v[198:201], v[92:95]
	v_mfma_f32_16x16x32_bf16 v[80:83], v[132:135], v[206:209], v[80:83]
	v_mfma_f32_16x16x32_bf16 v[76:79], v[158:161], v[206:209], v[76:79]
	v_mfma_f32_16x16x32_bf16 v[128:131], v[136:139], v[186:189], v[128:131]
	v_mfma_f32_16x16x32_bf16 v[124:127], v[162:165], v[186:189], v[124:127]
	v_mfma_f32_16x16x32_bf16 v[112:115], v[136:139], v[194:197], v[112:115]
	v_mfma_f32_16x16x32_bf16 v[108:111], v[162:165], v[194:197], v[108:111]
	v_mfma_f32_16x16x32_bf16 v[96:99], v[136:139], v[202:205], v[96:99]
	v_mfma_f32_16x16x32_bf16 v[92:95], v[162:165], v[202:205], v[92:95]
	v_mfma_f32_16x16x32_bf16 v[80:83], v[136:139], v[210:213], v[80:83]
	v_mfma_f32_16x16x32_bf16 v[76:79], v[162:165], v[210:213], v[76:79]
	s_setprio 0
	s_setprio 1
	v_mfma_f32_16x16x32_bf16 v[120:123], v[166:169], v[182:185], v[120:123]
	v_mfma_f32_16x16x32_bf16 v[116:119], v[174:177], v[182:185], v[116:119]
	v_mfma_f32_16x16x32_bf16 v[104:107], v[166:169], v[190:193], v[104:107]
	v_mfma_f32_16x16x32_bf16 v[100:103], v[174:177], v[190:193], v[100:103]
	v_mfma_f32_16x16x32_bf16 v[88:91], v[166:169], v[198:201], v[88:91]
	v_mfma_f32_16x16x32_bf16 v[84:87], v[174:177], v[198:201], v[84:87]
	v_mfma_f32_16x16x32_bf16 v[72:75], v[166:169], v[206:209], v[72:75]
	v_mfma_f32_16x16x32_bf16 v[68:71], v[174:177], v[206:209], v[68:71]
	v_mfma_f32_16x16x32_bf16 v[120:123], v[170:173], v[186:189], v[120:123]
	v_mfma_f32_16x16x32_bf16 v[116:119], v[178:181], v[186:189], v[116:119]
	v_mfma_f32_16x16x32_bf16 v[104:107], v[170:173], v[194:197], v[104:107]
	v_mfma_f32_16x16x32_bf16 v[100:103], v[178:181], v[194:197], v[100:103]
	v_mfma_f32_16x16x32_bf16 v[88:91], v[170:173], v[202:205], v[88:91]
	v_mfma_f32_16x16x32_bf16 v[84:87], v[178:181], v[202:205], v[84:87]
	v_mfma_f32_16x16x32_bf16 v[72:75], v[170:173], v[210:213], v[72:75]
	v_mfma_f32_16x16x32_bf16 v[68:71], v[178:181], v[210:213], v[68:71]
	s_setprio 0
	s_barrier
	s_add_i32 s34, s65, s47
	s_add_u32 s98, s42, s12
	s_addc_u32 s99, s43, s13
	s_mov_b32 m0, s34
	ds_read_b128 v[182:185], v156 offset:16384
	ds_read_b128 v[186:189], v156 offset:17408
	ds_read_b128 v[190:193], v156 offset:18432
	ds_read_b128 v[194:197], v156 offset:19456
	ds_read_b128 v[198:201], v156 offset:20480
	ds_read_b128 v[202:205], v156 offset:21504
	ds_read_b128 v[206:209], v156 offset:22528
	ds_read_b128 v[210:213], v156 offset:23552
	global_load_lds_dwordx4 v144, s[42:43]
	s_add_i32 m0, s34, 0x2000
	s_add_u32 s34, s42, 0x100000
	s_addc_u32 s35, s43, 0
	s_add_i32 s40, s66, s47
	global_load_lds_dwordx4 v140, s[42:43]
	s_mov_b32 m0, s40
	s_add_u32 s100, s38, s12
	s_addc_u32 s101, s39, s13
	global_load_lds_dwordx4 v144, s[34:35]
	s_add_i32 m0, s40, 0x2000
	s_nop 0
	global_load_lds_dwordx4 v140, s[34:35]
	s_mov_b32 m0, s50
	s_nop 0
	global_load_lds_dwordx4 v146, s[38:39]
	s_mov_b32 m0, s51
	s_nop 0
	global_load_lds_dwordx4 v142, s[38:39]
	s_waitcnt vmcnt(8)
	s_waitcnt lgkmcnt(0)
	s_barrier
	s_setprio 1
	s_waitcnt lgkmcnt(0)
	v_mfma_f32_16x16x32_bf16 v[64:67], v[132:135], v[182:185], v[64:67]
	v_mfma_f32_16x16x32_bf16 v[60:63], v[158:161], v[182:185], v[60:63]
	v_mfma_f32_16x16x32_bf16 v[48:51], v[132:135], v[190:193], v[48:51]
	v_mfma_f32_16x16x32_bf16 v[44:47], v[158:161], v[190:193], v[44:47]
	v_mfma_f32_16x16x32_bf16 v[32:35], v[132:135], v[198:201], v[32:35]
	v_mfma_f32_16x16x32_bf16 v[28:31], v[158:161], v[198:201], v[28:31]
	v_mfma_f32_16x16x32_bf16 v[16:19], v[132:135], v[206:209], v[16:19]
	v_mfma_f32_16x16x32_bf16 v[12:15], v[158:161], v[206:209], v[12:15]
	v_mfma_f32_16x16x32_bf16 v[64:67], v[136:139], v[186:189], v[64:67]
	v_mfma_f32_16x16x32_bf16 v[60:63], v[162:165], v[186:189], v[60:63]
	v_mfma_f32_16x16x32_bf16 v[48:51], v[136:139], v[194:197], v[48:51]
	v_mfma_f32_16x16x32_bf16 v[44:47], v[162:165], v[194:197], v[44:47]
	v_mfma_f32_16x16x32_bf16 v[32:35], v[136:139], v[202:205], v[32:35]
	v_mfma_f32_16x16x32_bf16 v[28:31], v[162:165], v[202:205], v[28:31]
	v_mfma_f32_16x16x32_bf16 v[16:19], v[136:139], v[210:213], v[16:19]
	v_mfma_f32_16x16x32_bf16 v[12:15], v[162:165], v[210:213], v[12:15]
	s_setprio 0
	s_setprio 1
	v_mfma_f32_16x16x32_bf16 v[56:59], v[166:169], v[182:185], v[56:59]
	v_mfma_f32_16x16x32_bf16 v[52:55], v[174:177], v[182:185], v[52:55]
	v_mfma_f32_16x16x32_bf16 v[40:43], v[166:169], v[190:193], v[40:43]
	v_mfma_f32_16x16x32_bf16 v[36:39], v[174:177], v[190:193], v[36:39]
	v_mfma_f32_16x16x32_bf16 v[24:27], v[166:169], v[198:201], v[24:27]
	v_mfma_f32_16x16x32_bf16 v[20:23], v[174:177], v[198:201], v[20:23]
	v_mfma_f32_16x16x32_bf16 v[8:11], v[166:169], v[206:209], v[8:11]
	v_mfma_f32_16x16x32_bf16 v[2:5], v[174:177], v[206:209], v[4:7]
	v_mfma_f32_16x16x32_bf16 v[56:59], v[170:173], v[186:189], v[56:59]
	v_mfma_f32_16x16x32_bf16 v[52:55], v[178:181], v[186:189], v[52:55]
	v_mfma_f32_16x16x32_bf16 v[40:43], v[170:173], v[194:197], v[40:43]
	v_mfma_f32_16x16x32_bf16 v[36:39], v[178:181], v[194:197], v[36:39]
	v_mfma_f32_16x16x32_bf16 v[24:27], v[170:173], v[202:205], v[24:27]
	v_mfma_f32_16x16x32_bf16 v[20:23], v[178:181], v[202:205], v[20:23]
	v_mfma_f32_16x16x32_bf16 v[8:11], v[170:173], v[210:213], v[8:11]
	v_mfma_f32_16x16x32_bf16 v[2:5], v[178:181], v[210:213], v[2:5]
	s_setprio 0
	s_barrier
; #define PG8_STAGE(bufoff, gbase, voff) do { _Pragma("unroll") for (int _i = 0; _i < 2; ++_i) \
;         __builtin_amdgcn_global_load_lds((const unsigned*)((const char*)(gbase) + (voff)[_i]), (LAS unsigned*)(lds + (bufoff) + ldsw + _i * 8192), 16, 0, 0); } while (0)
; #define PG8_LDA(dst, b, h) do { _Pragma("unroll") for (int m = 0; m < 4; ++m) _Pragma("unroll") for (int k = 0; k < 2; ++k) dst[m][k] = *(const LAS bf16x8*)(lds + PG8_SA(b, h) + aoff + m * 2048 + k * 1024); } while (0)
; #define PG8_LDB(dst, b, h) do { _Pragma("unroll") for (int n = 0; n < 2; ++n) _Pragma("unroll") for (int k = 0; k < 2; ++k) dst[n][k] = *(const LAS bf16x8*)(lds + PG8_SB(b, h) + boff + n * 2048 + k * 1024); } while (0)
; #define PG8_MMA(ai, bj, At, Bt) do { __builtin_amdgcn_s_setprio(1); _Pragma("unroll") for (int m = 0; m < 4; ++m) _Pragma("unroll") for (int n = 0; n < 2; ++n) _Pragma("unroll") for (int k = 0; k < 2; ++k) \
;         acc[ai][bj][m][n] = __builtin_amdgcn_mfma_f32_16x16x32_bf16(Bt[n][k], At[m][k], acc[ai][bj][m][n], 0, 0, 0); __builtin_amdgcn_s_setprio(0); } while (0)
; #define PG8_WAIT_V(n) asm volatile("s_waitcnt vmcnt(" #n ")" ::: "memory")
; #define PG8_WAIT_L(n) asm volatile("s_waitcnt lgkmcnt(" #n ")" ::: "memory")
; #define PG8_BAR __builtin_amdgcn_s_barrier()
; #define PG8_SCHED __builtin_amdgcn_sched_barrier(0)
; template <class Epi, class Sched, bool ALIGN_EPI = false, bool SP2 = false, bool TWOA = false, bool AGM = false>
; __device__ __forceinline__ void gemm_phase(LAS unsigned char* lds, const Gemm g, const Sched& S, const Epi& E, int wid) {
;     ...
;         for (int t = 0; t < nt; t += 2) {
;             const bool last = (t == nt - 2);
;     ...
;             PG8_LDB(B0, 1, 0); PG8_LDB(B1, 1, 1); PG8_SCHED; PG8_LDA(At, 1, 0); PG8_STAGE(PG8_SA(0, 1), a2 + hstepA, voffA);
;             PG8_WAIT_V(8); PG8_WAIT_L(0); PG8_BAR; PG8_MMA(0, 0, At, B0); PG8_MMA(0, 1, At, B1); PG8_BAR; PG8_SCHED;
;             PG8_LDA(At, 1, 1); PG8_STAGE(PG8_SB(1, 0), b3, voffB); PG8_STAGE(PG8_SB(1, 1), b3 + hstep, voffB); PG8_STAGE(PG8_SA(1, 0), a3, voffA);
;             PG8_WAIT_V(8); PG8_WAIT_L(0); PG8_BAR; PG8_MMA(1, 0, At, B0); PG8_MMA(1, 1, At, B1); PG8_BAR; PG8_SCHED;
	s_add_i32 s40, 0, 0x18000
	v_add_u32_e32 v1, s40, v153
	s_add_i32 s41, 0, 0x1c000
	ds_read_b128 v[132:135], v1
	ds_read_b128 v[136:139], v1 offset:1024
	ds_read_b128 v[158:161], v1 offset:2048
	ds_read_b128 v[162:165], v1 offset:3072
	v_add_u32_e32 v1, s41, v153
	ds_read_b128 v[166:169], v1
	ds_read_b128 v[170:173], v1 offset:1024
	ds_read_b128 v[174:177], v1 offset:2048
	ds_read_b128 v[178:181], v1 offset:3072
	s_add_u32 s34, s38, 0x80000
	s_addc_u32 s35, s39, 0
	s_mov_b32 m0, s52
	ds_read_b128 v[182:185], v156 offset:32768
	ds_read_b128 v[186:189], v156 offset:33792
	ds_read_b128 v[190:193], v156 offset:34816
	ds_read_b128 v[194:197], v156 offset:35840
	ds_read_b128 v[198:201], v156 offset:36864
	ds_read_b128 v[202:205], v156 offset:37888
	ds_read_b128 v[206:209], v156 offset:38912
	ds_read_b128 v[210:213], v156 offset:39936
	global_load_lds_dwordx4 v146, s[34:35]
	s_mov_b32 m0, s53
	s_nop 0
	global_load_lds_dwordx4 v142, s[34:35]
	s_waitcnt vmcnt(8)
	s_waitcnt lgkmcnt(0)
	s_barrier
	s_setprio 1
	s_waitcnt lgkmcnt(0)
	v_mfma_f32_16x16x32_bf16 v[128:131], v[132:135], v[182:185], v[128:131]
	v_mfma_f32_16x16x32_bf16 v[124:127], v[158:161], v[182:185], v[124:127]
	v_mfma_f32_16x16x32_bf16 v[112:115], v[132:135], v[190:193], v[112:115]
	v_mfma_f32_16x16x32_bf16 v[108:111], v[158:161], v[190:193], v[108:111]
	v_mfma_f32_16x16x32_bf16 v[96:99], v[132:135], v[198:201], v[96:99]
	v_mfma_f32_16x16x32_bf16 v[92:95], v[158:161], v[198:201], v[92:95]
	v_mfma_f32_16x16x32_bf16 v[80:83], v[132:135], v[206:209], v[80:83]
	v_mfma_f32_16x16x32_bf16 v[76:79], v[158:161], v[206:209], v[76:79]
	v_mfma_f32_16x16x32_bf16 v[128:131], v[136:139], v[186:189], v[128:131]
	v_mfma_f32_16x16x32_bf16 v[124:127], v[162:165], v[186:189], v[124:127]
	v_mfma_f32_16x16x32_bf16 v[112:115], v[136:139], v[194:197], v[112:115]
	v_mfma_f32_16x16x32_bf16 v[108:111], v[162:165], v[194:197], v[108:111]
	v_mfma_f32_16x16x32_bf16 v[96:99], v[136:139], v[202:205], v[96:99]
	v_mfma_f32_16x16x32_bf16 v[92:95], v[162:165], v[202:205], v[92:95]
	v_mfma_f32_16x16x32_bf16 v[80:83], v[136:139], v[210:213], v[80:83]
	v_mfma_f32_16x16x32_bf16 v[76:79], v[162:165], v[210:213], v[76:79]
	s_setprio 0
	s_setprio 1
	v_mfma_f32_16x16x32_bf16 v[120:123], v[166:169], v[182:185], v[120:123]
	v_mfma_f32_16x16x32_bf16 v[116:119], v[174:177], v[182:185], v[116:119]
	v_mfma_f32_16x16x32_bf16 v[104:107], v[166:169], v[190:193], v[104:107]
	v_mfma_f32_16x16x32_bf16 v[100:103], v[174:177], v[190:193], v[100:103]
	v_mfma_f32_16x16x32_bf16 v[88:91], v[166:169], v[198:201], v[88:91]
	v_mfma_f32_16x16x32_bf16 v[84:87], v[174:177], v[198:201], v[84:87]
	v_mfma_f32_16x16x32_bf16 v[72:75], v[166:169], v[206:209], v[72:75]
	v_mfma_f32_16x16x32_bf16 v[68:71], v[174:177], v[206:209], v[68:71]
	v_mfma_f32_16x16x32_bf16 v[120:123], v[170:173], v[186:189], v[120:123]
	v_mfma_f32_16x16x32_bf16 v[116:119], v[178:181], v[186:189], v[116:119]
	v_mfma_f32_16x16x32_bf16 v[104:107], v[170:173], v[194:197], v[104:107]
	v_mfma_f32_16x16x32_bf16 v[100:103], v[178:181], v[194:197], v[100:103]
	v_mfma_f32_16x16x32_bf16 v[88:91], v[170:173], v[202:205], v[88:91]
	v_mfma_f32_16x16x32_bf16 v[84:87], v[178:181], v[202:205], v[84:87]
	v_mfma_f32_16x16x32_bf16 v[72:75], v[170:173], v[210:213], v[72:75]
	v_mfma_f32_16x16x32_bf16 v[68:71], v[178:181], v[210:213], v[68:71]
	s_setprio 0
	s_barrier
	s_add_i32 s34, s40, s47
	s_mov_b32 m0, s34
	ds_read_b128 v[182:185], v156 offset:49152
	ds_read_b128 v[186:189], v156 offset:50176
	ds_read_b128 v[190:193], v156 offset:51200
	ds_read_b128 v[194:197], v156 offset:52224
	ds_read_b128 v[198:201], v156 offset:53248
	ds_read_b128 v[202:205], v156 offset:54272
	ds_read_b128 v[206:209], v156 offset:55296
	ds_read_b128 v[210:213], v156 offset:56320
	global_load_lds_dwordx4 v144, s[98:99]
	s_add_i32 m0, s34, 0x2000
	s_add_u32 s34, s42, 0x100080
	s_addc_u32 s35, s43, 0
	s_add_i32 s38, s41, s47
	global_load_lds_dwordx4 v140, s[98:99]
	s_mov_b32 m0, s38
	s_nop 0
	global_load_lds_dwordx4 v144, s[34:35]
	s_add_i32 m0, s38, 0x2000
	s_nop 0
	global_load_lds_dwordx4 v140, s[34:35]
	s_mov_b32 m0, s55
	s_nop 0
	global_load_lds_dwordx4 v146, s[100:101]
	s_mov_b32 m0, s56
	s_nop 0
	global_load_lds_dwordx4 v142, s[100:101]
	s_waitcnt vmcnt(8)
	s_waitcnt lgkmcnt(0)
	s_barrier
	s_setprio 1
	s_waitcnt lgkmcnt(0)
	v_mfma_f32_16x16x32_bf16 v[64:67], v[132:135], v[182:185], v[64:67]
	v_mfma_f32_16x16x32_bf16 v[60:63], v[158:161], v[182:185], v[60:63]
	v_mfma_f32_16x16x32_bf16 v[48:51], v[132:135], v[190:193], v[48:51]
	v_mfma_f32_16x16x32_bf16 v[44:47], v[158:161], v[190:193], v[44:47]
	v_mfma_f32_16x16x32_bf16 v[32:35], v[132:135], v[198:201], v[32:35]
	v_mfma_f32_16x16x32_bf16 v[28:31], v[158:161], v[198:201], v[28:31]
	v_mfma_f32_16x16x32_bf16 v[16:19], v[132:135], v[206:209], v[16:19]
	v_mfma_f32_16x16x32_bf16 v[12:15], v[158:161], v[206:209], v[12:15]
	v_mfma_f32_16x16x32_bf16 v[64:67], v[136:139], v[186:189], v[64:67]
	v_mfma_f32_16x16x32_bf16 v[60:63], v[162:165], v[186:189], v[60:63]
	v_mfma_f32_16x16x32_bf16 v[48:51], v[136:139], v[194:197], v[48:51]
	v_mfma_f32_16x16x32_bf16 v[44:47], v[162:165], v[194:197], v[44:47]
	v_mfma_f32_16x16x32_bf16 v[32:35], v[136:139], v[202:205], v[32:35]
	v_mfma_f32_16x16x32_bf16 v[28:31], v[162:165], v[202:205], v[28:31]
	v_mfma_f32_16x16x32_bf16 v[16:19], v[136:139], v[210:213], v[16:19]
	v_mfma_f32_16x16x32_bf16 v[12:15], v[162:165], v[210:213], v[12:15]
	s_setprio 0
	s_setprio 1
	v_mfma_f32_16x16x32_bf16 v[56:59], v[166:169], v[182:185], v[56:59]
	v_mfma_f32_16x16x32_bf16 v[52:55], v[174:177], v[182:185], v[52:55]
	v_mfma_f32_16x16x32_bf16 v[40:43], v[166:169], v[190:193], v[40:43]
	v_mfma_f32_16x16x32_bf16 v[36:39], v[174:177], v[190:193], v[36:39]
	v_mfma_f32_16x16x32_bf16 v[24:27], v[166:169], v[198:201], v[24:27]
	v_mfma_f32_16x16x32_bf16 v[20:23], v[174:177], v[198:201], v[20:23]
	v_mfma_f32_16x16x32_bf16 v[6:9], v[166:169], v[206:209], v[8:11]
	v_mfma_f32_16x16x32_bf16 v[2:5], v[174:177], v[206:209], v[2:5]
	v_mfma_f32_16x16x32_bf16 v[56:59], v[170:173], v[186:189], v[56:59]
	v_mfma_f32_16x16x32_bf16 v[52:55], v[178:181], v[186:189], v[52:55]
	v_mfma_f32_16x16x32_bf16 v[40:43], v[170:173], v[194:197], v[40:43]
	v_mfma_f32_16x16x32_bf16 v[36:39], v[178:181], v[194:197], v[36:39]
	v_mfma_f32_16x16x32_bf16 v[24:27], v[170:173], v[202:205], v[24:27]
	v_mfma_f32_16x16x32_bf16 v[20:23], v[178:181], v[202:205], v[20:23]
	v_mfma_f32_16x16x32_bf16 v[8:11], v[170:173], v[210:213], v[6:9]
	v_mfma_f32_16x16x32_bf16 v[4:7], v[178:181], v[210:213], v[2:5]
	s_setprio 0
	s_barrier
	s_add_u32 s36, s36, 0x100
	s_addc_u32 s37, s37, 0
	s_cmp_gt_u32 s73, 61
	s_cbranch_scc1 .LBB0_829
